# cache-policy hint: nt on the write-once f32 K/V window-output stores of the QKV epilogue (32 stores)
# speedup vs baseline: 1.0055x; 1.0055x over previous
; #define EPI_ROWS(...) _Pragma("unroll") for (int ai = 0; ai < 2; ++ai) _Pragma("unroll") for (int m = 0; m < 4; ++m) { const int rr = ai * 128 + wr * 64 + m * 16 + fr; __VA_ARGS__ }
; #define EPI_COLS8(...) _Pragma("unroll") for (int bj = 0; bj < 2; ++bj) { const int cc = bj * 128 + wc * 32 + 8 * fq; const f32x4 v0 = acc[ai][bj][m][0], v1 = acc[ai][bj][m][1]; __VA_ARGS__ }
;     DI void operator()(const Acc& acc, int wr, int wc, int fr, int fq) const {
;     ...
;         float* op = out + (which == 1 ? O_KP : O_VP); float* os = out + (which == 1 ? O_KS : O_VS);
;         EPI_ROWS(const int row = row0 + rr;
;             EPI_COLS8(const int col = cb + cc; u32x4 w; w.x = pk2(v0[0] * sc, v0[1] * sc); w.y = pk2(v0[2] * sc, v0[3] * sc); w.z = pk2(v1[0] * sc, v1[1] * sc); w.w = pk2(v1[2] * sc, v1[3] * sc);
;                 *(u32x4*)(dst + (size_t)row * 1024 + col) = w;
;                 if (which != 0) {
;                     if (row < NP) { const int tb = row & (TP - 1); if (tb >= TP - 2048) { float* o = op + ((size_t)(row >> 13) * 2048 + (tb - (TP - 2048))) * 1024 + col; *(f32x4*)o = v0; *(f32x4*)(o + 4) = v1; } }
;                     else if (row < NT) { float* o = os + (size_t)(row - NP) * 1024 + col; *(f32x4*)o = v0; *(f32x4*)(o + 4) = v1; }
.LBB0_1255:
	v_lshl_add_u64 v[142:143], v[134:135], 2, v[142:143]
	global_store_dwordx4 v[142:143], v[124:127], off nt
	global_store_dwordx4 v[142:143], v[120:123], off offset:16 nt

;     DI void operator()(const Acc& acc, int wr, int wc, int fr, int fq) const {
;     ...
;                     if (row < NP) { const int tb = row & (TP - 1); if (tb >= TP - 2048) { float* o = op + ((size_t)(row >> 13) * 2048 + (tb - (TP - 2048))) * 1024 + col; *(f32x4*)o = v0; *(f32x4*)(o + 4) = v1; } }
.LBB0_1261:
	v_lshl_add_u64 v[120:121], v[134:135], 2, v[136:137]
	global_store_dwordx4 v[120:121], v[116:119], off offset:512 nt
	global_store_dwordx4 v[120:121], v[112:115], off offset:528 nt

;     DI void operator()(const Acc& acc, int wr, int wc, int fr, int fq) const {
;     ...
;                     if (row < NP) { const int tb = row & (TP - 1); if (tb >= TP - 2048) { float* o = op + ((size_t)(row >> 13) * 2048 + (tb - (TP - 2048))) * 1024 + col; *(f32x4*)o = v0; *(f32x4*)(o + 4) = v1; } }
.LBB0_1267:
	v_lshl_add_u64 v[118:119], v[134:135], 2, v[118:119]
	global_store_dwordx4 v[118:119], v[108:111], off nt
	global_store_dwordx4 v[118:119], v[104:107], off offset:16 nt

;     DI void operator()(const Acc& acc, int wr, int wc, int fr, int fq) const {
;     ...
;                     if (row < NP) { const int tb = row & (TP - 1); if (tb >= TP - 2048) { float* o = op + ((size_t)(row >> 13) * 2048 + (tb - (TP - 2048))) * 1024 + col; *(f32x4*)o = v0; *(f32x4*)(o + 4) = v1; } }
.LBB0_1273:
	v_lshl_add_u64 v[104:105], v[134:135], 2, v[112:113]
	global_store_dwordx4 v[104:105], v[100:103], off offset:512 nt
	global_store_dwordx4 v[104:105], v[96:99], off offset:528 nt

;     DI void operator()(const Acc& acc, int wr, int wc, int fr, int fq) const {
;     ...
;                     if (row < NP) { const int tb = row & (TP - 1); if (tb >= TP - 2048) { float* o = op + ((size_t)(row >> 13) * 2048 + (tb - (TP - 2048))) * 1024 + col; *(f32x4*)o = v0; *(f32x4*)(o + 4) = v1; } }
.LBB0_1279:
	v_lshl_add_u64 v[102:103], v[134:135], 2, v[102:103]
	global_store_dwordx4 v[102:103], v[92:95], off nt
	global_store_dwordx4 v[102:103], v[88:91], off offset:16 nt

;     DI void operator()(const Acc& acc, int wr, int wc, int fr, int fq) const {
;     ...
;                     if (row < NP) { const int tb = row & (TP - 1); if (tb >= TP - 2048) { float* o = op + ((size_t)(row >> 13) * 2048 + (tb - (TP - 2048))) * 1024 + col; *(f32x4*)o = v0; *(f32x4*)(o + 4) = v1; } }
.LBB0_1285:
	v_lshl_add_u64 v[88:89], v[134:135], 2, v[96:97]
	global_store_dwordx4 v[88:89], v[84:87], off offset:512 nt
	global_store_dwordx4 v[88:89], v[80:83], off offset:528 nt

;     DI void operator()(const Acc& acc, int wr, int wc, int fr, int fq) const {
;     ...
;                     if (row < NP) { const int tb = row & (TP - 1); if (tb >= TP - 2048) { float* o = op + ((size_t)(row >> 13) * 2048 + (tb - (TP - 2048))) * 1024 + col; *(f32x4*)o = v0; *(f32x4*)(o + 4) = v1; } }
.LBB0_1291:
	v_lshl_add_u64 v[86:87], v[134:135], 2, v[86:87]
	global_store_dwordx4 v[86:87], v[76:79], off nt
	global_store_dwordx4 v[86:87], v[72:75], off offset:16 nt

;     DI void operator()(const Acc& acc, int wr, int wc, int fr, int fq) const {
;     ...
;                     if (row < NP) { const int tb = row & (TP - 1); if (tb >= TP - 2048) { float* o = op + ((size_t)(row >> 13) * 2048 + (tb - (TP - 2048))) * 1024 + col; *(f32x4*)o = v0; *(f32x4*)(o + 4) = v1; } }
.LBB0_1297:
	v_lshl_add_u64 v[72:73], v[134:135], 2, v[80:81]
	global_store_dwordx4 v[72:73], v[68:71], off offset:512 nt
	global_store_dwordx4 v[72:73], v[64:67], off offset:528 nt

;     DI void operator()(const Acc& acc, int wr, int wc, int fr, int fq) const {
;     ...
;                     if (row < NP) { const int tb = row & (TP - 1); if (tb >= TP - 2048) { float* o = op + ((size_t)(row >> 13) * 2048 + (tb - (TP - 2048))) * 1024 + col; *(f32x4*)o = v0; *(f32x4*)(o + 4) = v1; } }
.LBB0_1303:
	v_lshl_add_u64 v[70:71], v[134:135], 2, v[70:71]
	global_store_dwordx4 v[70:71], v[60:63], off nt
	global_store_dwordx4 v[70:71], v[56:59], off offset:16 nt

;     DI void operator()(const Acc& acc, int wr, int wc, int fr, int fq) const {
;     ...
;                     if (row < NP) { const int tb = row & (TP - 1); if (tb >= TP - 2048) { float* o = op + ((size_t)(row >> 13) * 2048 + (tb - (TP - 2048))) * 1024 + col; *(f32x4*)o = v0; *(f32x4*)(o + 4) = v1; } }
.LBB0_1309:
	v_lshl_add_u64 v[56:57], v[134:135], 2, v[64:65]
	global_store_dwordx4 v[56:57], v[52:55], off offset:512 nt
	global_store_dwordx4 v[56:57], v[48:51], off offset:528 nt

;     DI void operator()(const Acc& acc, int wr, int wc, int fr, int fq) const {
;     ...
;                     if (row < NP) { const int tb = row & (TP - 1); if (tb >= TP - 2048) { float* o = op + ((size_t)(row >> 13) * 2048 + (tb - (TP - 2048))) * 1024 + col; *(f32x4*)o = v0; *(f32x4*)(o + 4) = v1; } }
.LBB0_1315:
	v_lshl_add_u64 v[54:55], v[134:135], 2, v[54:55]
	global_store_dwordx4 v[54:55], v[44:47], off nt
	global_store_dwordx4 v[54:55], v[40:43], off offset:16 nt

;     DI void operator()(const Acc& acc, int wr, int wc, int fr, int fq) const {
;     ...
;                     if (row < NP) { const int tb = row & (TP - 1); if (tb >= TP - 2048) { float* o = op + ((size_t)(row >> 13) * 2048 + (tb - (TP - 2048))) * 1024 + col; *(f32x4*)o = v0; *(f32x4*)(o + 4) = v1; } }
.LBB0_1321:
	v_lshl_add_u64 v[40:41], v[134:135], 2, v[48:49]
	global_store_dwordx4 v[40:41], v[36:39], off offset:512 nt
	global_store_dwordx4 v[40:41], v[32:35], off offset:528 nt

;     DI void operator()(const Acc& acc, int wr, int wc, int fr, int fq) const {
;     ...
;                     if (row < NP) { const int tb = row & (TP - 1); if (tb >= TP - 2048) { float* o = op + ((size_t)(row >> 13) * 2048 + (tb - (TP - 2048))) * 1024 + col; *(f32x4*)o = v0; *(f32x4*)(o + 4) = v1; } }
.LBB0_1327:
	v_lshl_add_u64 v[38:39], v[134:135], 2, v[38:39]
	global_store_dwordx4 v[38:39], v[28:31], off nt
	global_store_dwordx4 v[38:39], v[24:27], off offset:16 nt

;     DI void operator()(const Acc& acc, int wr, int wc, int fr, int fq) const {
;     ...
;                     if (row < NP) { const int tb = row & (TP - 1); if (tb >= TP - 2048) { float* o = op + ((size_t)(row >> 13) * 2048 + (tb - (TP - 2048))) * 1024 + col; *(f32x4*)o = v0; *(f32x4*)(o + 4) = v1; } }
.LBB0_1333:
	v_lshl_add_u64 v[24:25], v[134:135], 2, v[32:33]
	global_store_dwordx4 v[24:25], v[20:23], off offset:512 nt
	global_store_dwordx4 v[24:25], v[16:19], off offset:528 nt

;     DI void operator()(const Acc& acc, int wr, int wc, int fr, int fq) const {
;     ...
;                     if (row < NP) { const int tb = row & (TP - 1); if (tb >= TP - 2048) { float* o = op + ((size_t)(row >> 13) * 2048 + (tb - (TP - 2048))) * 1024 + col; *(f32x4*)o = v0; *(f32x4*)(o + 4) = v1; } }
.LBB0_1339:
	v_lshl_add_u64 v[22:23], v[134:135], 2, v[22:23]
	global_store_dwordx4 v[22:23], v[12:15], off nt
	global_store_dwordx4 v[22:23], v[8:11], off offset:16 nt

;     DI void operator()(const Acc& acc, int wr, int wc, int fr, int fq) const {
;     ...
;                     if (row < NP) { const int tb = row & (TP - 1); if (tb >= TP - 2048) { float* o = op + ((size_t)(row >> 13) * 2048 + (tb - (TP - 2048))) * 1024 + col; *(f32x4*)o = v0; *(f32x4*)(o + 4) = v1; } }
.LBB0_1345:
	v_lshl_add_u64 v[8:9], v[134:135], 2, v[16:17]
	global_store_dwordx4 v[8:9], v[4:7], off offset:512 nt
	global_store_dwordx4 v[8:9], v[0:3], off offset:528 nt
